# static wave-half priority (no per-segment toggling) in all four GEMM K-loops (E, A, F, D)
# speedup vs baseline: 1.0067x; 1.0027x over previous
; #define PG8_STAGE(bufoff, gbase, voff) do { _Pragma("unroll") for (int _i = 0; _i < 2; ++_i) \
;         __builtin_amdgcn_global_load_lds((const unsigned*)((const char*)(gbase) + (voff)[_i]), (LAS unsigned*)(lds + (bufoff) + ldsw + _i * 8192), 16, 0, 0); } while (0)
; #define PG8_WAIT_V(n) asm volatile("s_waitcnt vmcnt(" #n ")" ::: "memory")
; #define PG8_BAR __builtin_amdgcn_s_barrier()
; template <class Epi>
; __device__ __forceinline__ void gemm_phase(LAS unsigned char* lds, const Gemm g, const StaticOrder& S, const Epi& E) {
;     int tid = threadIdx.x; asm volatile("" : "+v"(tid));
;     const int wid = __builtin_amdgcn_readfirstlane(tid >> 6), lane = tid & 63, wr = wid >> 2, wc = wid & 3, fr = lane & 15, fq = lane >> 4;
;     const int K = g.K, nt = K / BK;
;     unsigned voffA[2], voffB[2];
; #pragma unroll
;     for (int i = 0; i < 2; ++i) { int R, C; stage_rc(tid * 16 + i * 8192, R, C); const int Rb = Epi::PERM ? ((R & ~31) + perm32(R & 31)) : R;
;         voffA[i] = (unsigned)(R * K + C) * 2u; voffB[i] = (unsigned)(Rb * K + C) * 2u; }
;     const size_t kstep = (size_t)(BK * 2);
;     const size_t hstep = (size_t)HALF * K * 2;
;     const size_t tstep = 2 * hstep;
;     const unsigned ldsw = (unsigned)wid * 1024u;
;     const int aoff = lds_byte(wr * 64 + fr, fq * 8), boff = lds_byte(wc * 32 + fr, fq * 8);
;     ...
;     Unit cur, nxt; int ui = 0;
;     if (!S.next(0, cur)) return;
;     f32x4 acc[2][2][4][2];
; #pragma unroll
;     for (int a = 0; a < 2; ++a)
; #pragma unroll
;         for (int b = 0; b < 2; ++b)
; #pragma unroll
;             for (int m = 0; m < 4; ++m)
; #pragma unroll
;                 for (int n = 0; n < 2; ++n) acc[a][b][m][n] = (f32x4){0.f, 0.f, 0.f, 0.f};
;     bf16x8 At[4][2], B0[2][2], B1[2][2];
;     const char* cA = (const char*)g.A + (size_t)cur.pm * tstep; const char* cB = (const char*)g.Bt + (size_t)cur.pn * tstep;
;     PG8_STAGE(PG8_SB(0, 0), cB, voffB); PG8_STAGE(PG8_SA(0, 0), cA, voffA); PG8_STAGE(PG8_SB(0, 1), cB + hstep, voffB); PG8_STAGE(PG8_SA(0, 1), cA + hstep, voffA);
;     if (wr == 1) PG8_BAR;
;     PG8_WAIT_V(4); PG8_BAR;
;     PG8_STAGE(PG8_SB(1, 0), cB + kstep, voffB); PG8_STAGE(PG8_SA(1, 0), cA + kstep, voffA); PG8_STAGE(PG8_SB(1, 1), cB + hstep + kstep, voffB);
;     PG8_WAIT_V(6); PG8_BAR;
.LBB0_87:
	s_mul_hi_i32 s4, s18, 0x92492493
	s_add_i32 s4, s4, s18
	s_lshr_b32 s5, s4, 31
	s_ashr_i32 s4, s4, 2
	s_add_i32 s22, s4, s5
	s_mul_i32 s4, s22, 7
	s_sub_i32 s88, s18, s4
	s_ashr_i32 s23, s22, 31
	s_cmp_lt_i32 s88, 3
	s_mov_b64 s[4:5], -1
	s_cbranch_scc1 .LBB0_235
	s_cmp_lt_i32 s88, 5
	s_cbranch_scc1 .LBB0_176
	s_lshl_b64 s[4:5], s[22:23], 23
	v_writelane_b32 v252, s4, 4
	s_cmp_lt_i32 s88, 6
	s_mov_b64 s[6:7], -1
	v_writelane_b32 v252, s5, 5
	s_cbranch_scc1 .LBB0_124
	s_cmp_eq_u32 s88, 6
	s_cbranch_scc0 .LBB0_123
	v_readlane_b32 s4, v253, 56
	v_mov_b32_e32 v10, v167
	v_readlane_b32 s5, v253, 57
	s_andn2_b64 vcc, exec, s[4:5]
	v_readfirstlane_b32 s10, v10
	s_cbranch_vccnz .LBB0_123
	v_lshlrev_b32_e32 v0, 4, v10
	v_add_u32_e32 v2, 0x2000, v0
	v_ashrrev_i32_e32 v3, 31, v2
	v_lshrrev_b32_e32 v3, 22, v3
	v_add_u32_e32 v3, v2, v3
	v_ashrrev_i32_e32 v11, 10, v3
	v_mul_i32_i24_e32 v3, 0x400, v11
	v_sub_u32_e32 v2, v2, v3
	v_lshrrev_b32_e32 v3, 4, v2
	v_bitop3_b32 v2, v3, v2, 32 bitop3:0x6c
	v_ashrrev_i32_e32 v3, 31, v2
	v_lshrrev_b32_e32 v3, 26, v3
	v_add_u32_e32 v3, v2, v3
	v_lshlrev_b32_e32 v4, 3, v11
	v_ashrrev_i32_e32 v12, 6, v3
	v_and_b32_e32 v4, -16, v4
	v_add_u32_e32 v4, v12, v4
	v_and_b32_e32 v5, 3, v12
	s_mov_b32 s6, 0x7ffe0
	v_lshrrev_b32_e32 v6, 2, v4
	v_lshlrev_b32_e32 v7, 1, v4
	v_and_b32_e32 v3, 0xc0, v3
	v_and_or_b32 v5, v4, s6, v5
	v_and_b32_e32 v6, 4, v6
	v_and_b32_e32 v7, 24, v7
	v_sub_u32_e32 v2, v2, v3
	v_or3_b32 v5, v5, v6, v7
	v_lshlrev_b32_e32 v6, 5, v11
	v_ashrrev_i16_sdwa v2, v188, sext(v2) dst_sel:DWORD dst_unused:UNUSED_PAD src0_sel:DWORD src1_sel:BYTE_0
	v_and_b32_e32 v6, 32, v6
	v_bfe_i32 v13, v2, 0, 16
	v_add_lshl_u32 v2, v6, v13, 1
	v_lshl_add_u32 v138, v5, 13, v2
	v_lshl_add_u32 v140, v4, 13, v2
	v_bfe_i32 v2, v10, 27, 1
	v_lshrrev_b32_e32 v2, 22, v2
	v_add_u32_e32 v2, v0, v2
	v_and_b32_e32 v2, 0xfffffc00, v2
	v_sub_u32_e32 v0, v0, v2
	v_lshrrev_b32_e32 v2, 4, v0
	v_ashrrev_i32_e32 v3, 31, v10
	v_bitop3_b32 v0, v2, v0, 32 bitop3:0x6c
	v_lshrrev_b32_e32 v3, 26, v3
	v_ashrrev_i32_e32 v2, 31, v0
	v_add_u32_e32 v3, v10, v3
	v_writelane_b32 v252, s88, 6
	s_waitcnt lgkmcnt(0)
	s_add_u32 s55, s94, 0xa0b0000
	v_lshrrev_b32_e32 v2, 26, v2
	v_ashrrev_i32_e32 v15, 6, v3
	s_addc_u32 s88, s95, 0
	v_readlane_b32 s4, v252, 4
	v_add_u32_e32 v2, v0, v2
	v_lshlrev_b32_e32 v3, 3, v15
	v_readlane_b32 s5, v252, 5
	s_add_u32 s4, s94, s4
	v_ashrrev_i32_e32 v14, 6, v2
	v_and_b32_e32 v3, -16, v3
	s_addc_u32 s5, s95, s5
	v_add_u32_e32 v3, v14, v3
	s_add_u32 s89, s4, 0x3600000
	v_and_b32_e32 v4, 3, v14
	v_lshrrev_b32_e32 v5, 2, v3
	v_lshlrev_b32_e32 v6, 1, v3
	v_and_b32_e32 v2, 0xc0, v2
	s_addc_u32 s90, s5, 0
	s_ashr_i32 s5, s10, 6
	v_and_or_b32 v4, v3, s6, v4
	v_and_b32_e32 v5, 4, v5
	v_and_b32_e32 v6, 24, v6
	v_sub_u32_e32 v0, v0, v2
	s_ashr_i32 s4, s10, 8
	s_lshl_b32 s91, s5, 10
	v_or3_b32 v4, v4, v5, v6
	v_lshlrev_b32_e32 v5, 5, v15
	v_ashrrev_i16_sdwa v0, v188, sext(v0) dst_sel:DWORD dst_unused:UNUSED_PAD src0_sel:DWORD src1_sel:BYTE_0
	v_readlane_b32 s6, v254, 9
	v_and_b32_e32 v5, 32, v5
	v_bfe_i32 v16, v0, 0, 16
	v_readlane_b32 s7, v254, 10
	s_add_u32 s6, s89, s6
	v_add_lshl_u32 v2, v5, v16, 1
	s_addc_u32 s7, s90, s7
	s_add_i32 s92, s91, 0
	v_lshl_add_u32 v0, v4, 13, v2
	s_add_i32 m0, s92, 0x10000
	v_readlane_b32 s8, v254, 32
	global_load_lds_dwordx4 v0, s[6:7]
	s_add_i32 m0, s92, 0x12000
	v_readlane_b32 s9, v254, 33
	s_add_u32 s46, s55, s8
	v_lshl_add_u32 v142, v3, 13, v2
	global_load_lds_dwordx4 v138, s[6:7]
	s_addc_u32 s47, s88, s9
	s_mov_b32 m0, s92
	s_add_i32 s93, s92, 0x2000
	global_load_lds_dwordx4 v142, s[46:47]
	s_mov_b32 m0, s93
	s_add_u32 s8, s6, 0x100000
	global_load_lds_dwordx4 v140, s[46:47]
	s_addc_u32 s9, s7, 0
	s_add_i32 m0, s92, 0x14000
	v_mov_b32_e32 v139, v1
	global_load_lds_dwordx4 v0, s[8:9]
	s_add_i32 m0, s92, 0x16000
	v_mov_b32_e32 v143, v1
	global_load_lds_dwordx4 v138, s[8:9]
	s_add_u32 s8, s46, 0x100000
	s_addc_u32 s9, s47, 0
	s_add_i32 s96, s92, 0x4000
	s_mov_b32 m0, s96
	s_add_i32 s97, s92, 0x6000
	global_load_lds_dwordx4 v142, s[8:9]
	s_mov_b32 m0, s97
	v_mov_b32_e32 v141, v1
	global_load_lds_dwordx4 v140, s[8:9]
	v_lshl_add_u64 v[8:9], s[6:7], 0, v[0:1]
	v_lshl_add_u64 v[6:7], s[6:7], 0, v[138:139]
	v_lshl_add_u64 v[4:5], s[46:47], 0, v[142:143]
	s_cmp_lg_u32 s4, 1
	v_lshl_add_u64 v[2:3], s[46:47], 0, v[140:141]
	s_mov_b32 s70, s10
	s_cbranch_scc1 .LBB0_94
	s_barrier
	s_setprio 1

; #define PG8_STAGE(bufoff, gbase, voff) do { _Pragma("unroll") for (int _i = 0; _i < 2; ++_i) \
;         __builtin_amdgcn_global_load_lds((const unsigned*)((const char*)(gbase) + (voff)[_i]), (LAS unsigned*)(lds + (bufoff) + ldsw + _i * 8192), 16, 0, 0); } while (0)
; #define PG8_LDA(dst, b, h) do { _Pragma("unroll") for (int m = 0; m < 4; ++m) _Pragma("unroll") for (int k = 0; k < 2; ++k) dst[m][k] = *(const LAS bf16x8*)(lds + PG8_SA(b, h) + aoff + m * 2048 + k * 1024); } while (0)
; #define PG8_LDB(dst, b, h) do { _Pragma("unroll") for (int n = 0; n < 2; ++n) _Pragma("unroll") for (int k = 0; k < 2; ++k) dst[n][k] = *(const LAS bf16x8*)(lds + PG8_SB(b, h) + boff + n * 2048 + k * 1024); } while (0)
; #define PG8_WAIT_V(n) asm volatile("s_waitcnt vmcnt(" #n ")" ::: "memory")
; #define PG8_WAIT_L(n) asm volatile("s_waitcnt lgkmcnt(" #n ")" ::: "memory")
; #define PG8_BAR __builtin_amdgcn_s_barrier()
; #define PG8_SCHED __builtin_amdgcn_sched_barrier(0)
; template <class Epi>
; __device__ __forceinline__ void gemm_phase(LAS unsigned char* lds, const Gemm g, const StaticOrder& S, const Epi& E) {
;     ...
;             PG8_LDB(B0, 0, 0); PG8_SCHED; PG8_LDA(At, 0, 0); PG8_STAGE(PG8_SA(1, 1), a1 + hstep, voffA);
;             PG8_WAIT_L(8); PG8_BAR; PG8_WAIT_L(0); PG8_MMA(0, 0, At, B0); PG8_BAR; PG8_SCHED;
;             PG8_LDB(B1, 0, 1); PG8_STAGE(PG8_SB(0, 0), b2, voffB);
;             PG8_BAR; PG8_WAIT_L(0); PG8_MMA(0, 1, At, B1); PG8_BAR;
;             PG8_LDA(At, 0, 1); PG8_STAGE(PG8_SA(0, 0), a2, voffA);
;             PG8_BAR; PG8_WAIT_L(0); PG8_MMA(1, 0, At, B0); PG8_BAR; PG8_SCHED;
;             PG8_STAGE(PG8_SB(0, 1), b2 + hstep, voffB);
;             PG8_WAIT_V(6); PG8_BAR; PG8_MMA(1, 1, At, B1); PG8_BAR;
;             PG8_LDB(B0, 1, 0); PG8_SCHED; PG8_LDA(At, 1, 0); PG8_STAGE(PG8_SA(0, 1), a2 + hstep, voffA);
;             PG8_WAIT_L(8); PG8_BAR; PG8_WAIT_L(0); PG8_MMA(0, 0, At, B0); PG8_BAR; PG8_SCHED;
;             PG8_LDB(B1, 1, 1); PG8_STAGE(PG8_SB(1, 0), b3, voffB);
;             PG8_BAR; PG8_WAIT_L(0); PG8_MMA(0, 1, At, B1); PG8_BAR;
;             PG8_LDA(At, 1, 1); PG8_STAGE(PG8_SA(1, 0), a3, voffA);
;             PG8_BAR; PG8_WAIT_L(0); PG8_MMA(1, 0, At, B0); PG8_BAR; PG8_SCHED;
;             PG8_STAGE(PG8_SB(1, 1), b3 + hstep, voffB);
;             PG8_WAIT_V(6); PG8_BAR; PG8_MMA(1, 1, At, B1); PG8_BAR;
.LBB0_103:
	s_add_u32 s5, s46, 0xfff00080
	s_addc_u32 s6, s47, -1
	s_add_i32 s58, 0, 0x10000
	v_add_u32_e32 v152, s58, v157
	ds_read_b128 v[130:133], v152
	ds_read_b128 v[134:137], v152 offset:1024
	ds_read_b128 v[148:151], v152 offset:2048
	ds_read_b128 v[152:155], v152 offset:3072
	s_cmp_eq_u32 s4, 60
	s_cselect_b32 s49, s25, s6
	s_cselect_b32 s48, s71, s5
	s_cselect_b32 s7, s13, vcc_hi
	s_cselect_b32 s6, s87, vcc_lo
	s_add_i32 m0, s92, 0xc000
	ds_read_b128 v[170:173], v168
	ds_read_b128 v[174:177], v168 offset:1024
	ds_read_b128 v[178:181], v168 offset:2048
	ds_read_b128 v[182:185], v168 offset:3072
	ds_read_b128 v[204:207], v168 offset:4096
	ds_read_b128 v[208:211], v168 offset:5120
	ds_read_b128 v[212:215], v168 offset:6144
	ds_read_b128 v[216:219], v168 offset:7168
	global_load_lds_dwordx4 v144, s[46:47]
	s_add_i32 m0, s92, 0xe000
	s_nop 0
	global_load_lds_dwordx4 v146, s[46:47]
	s_waitcnt lgkmcnt(8)
	s_barrier
	s_waitcnt lgkmcnt(0)
	s_waitcnt lgkmcnt(0)
	v_mfma_f32_16x16x32_bf16 v[126:129], v[130:133], v[170:173], v[126:129]
	v_mfma_f32_16x16x32_bf16 v[122:125], v[148:151], v[170:173], v[122:125]
	v_mfma_f32_16x16x32_bf16 v[110:113], v[130:133], v[178:181], v[110:113]
	v_mfma_f32_16x16x32_bf16 v[106:109], v[148:151], v[178:181], v[106:109]
	v_mfma_f32_16x16x32_bf16 v[94:97], v[130:133], v[204:207], v[94:97]
	v_mfma_f32_16x16x32_bf16 v[90:93], v[148:151], v[204:207], v[90:93]
	v_mfma_f32_16x16x32_bf16 v[78:81], v[130:133], v[212:215], v[78:81]
	v_mfma_f32_16x16x32_bf16 v[74:77], v[148:151], v[212:215], v[74:77]
	v_mfma_f32_16x16x32_bf16 v[126:129], v[134:137], v[174:177], v[126:129]
	v_mfma_f32_16x16x32_bf16 v[122:125], v[152:155], v[174:177], v[122:125]
	v_mfma_f32_16x16x32_bf16 v[110:113], v[134:137], v[182:185], v[110:113]
	v_mfma_f32_16x16x32_bf16 v[106:109], v[152:155], v[182:185], v[106:109]
	v_mfma_f32_16x16x32_bf16 v[94:97], v[134:137], v[208:211], v[94:97]
	v_mfma_f32_16x16x32_bf16 v[90:93], v[152:155], v[208:211], v[90:93]
	v_mfma_f32_16x16x32_bf16 v[78:81], v[134:137], v[216:219], v[78:81]
	v_mfma_f32_16x16x32_bf16 v[74:77], v[152:155], v[216:219], v[74:77]
	s_barrier
	s_add_i32 s5, 0, 0x14000
	v_add_u32_e32 v162, s5, v157
	s_add_i32 s58, s58, s91
	ds_read_b128 v[226:229], v162
	ds_read_b128 v[230:233], v162 offset:1024
	ds_read_b128 v[234:237], v162 offset:2048
	ds_read_b128 v[238:241], v162 offset:3072
	s_add_u32 s100, s6, s26
	s_addc_u32 s101, s7, s27
	s_mov_b32 m0, s58
	s_nop 0
	global_load_lds_dwordx4 v0, s[6:7]
	s_add_i32 m0, s58, 0x2000
	s_nop 0
	global_load_lds_dwordx4 v138, s[6:7]
	s_barrier
	s_waitcnt lgkmcnt(0)
	s_waitcnt lgkmcnt(0)
	v_mfma_f32_16x16x32_bf16 v[118:121], v[226:229], v[170:173], v[118:121]
	v_mfma_f32_16x16x32_bf16 v[114:117], v[234:237], v[170:173], v[114:117]
	v_mfma_f32_16x16x32_bf16 v[102:105], v[226:229], v[178:181], v[102:105]
	v_mfma_f32_16x16x32_bf16 v[98:101], v[234:237], v[178:181], v[98:101]
	v_mfma_f32_16x16x32_bf16 v[86:89], v[226:229], v[204:207], v[86:89]
	v_mfma_f32_16x16x32_bf16 v[82:85], v[234:237], v[204:207], v[82:85]
	v_mfma_f32_16x16x32_bf16 v[70:73], v[226:229], v[212:215], v[70:73]
	v_mfma_f32_16x16x32_bf16 v[66:69], v[234:237], v[212:215], v[66:69]
	v_mfma_f32_16x16x32_bf16 v[118:121], v[230:233], v[174:177], v[118:121]
	v_mfma_f32_16x16x32_bf16 v[114:117], v[238:241], v[174:177], v[114:117]
	v_mfma_f32_16x16x32_bf16 v[102:105], v[230:233], v[182:185], v[102:105]
	v_mfma_f32_16x16x32_bf16 v[98:101], v[238:241], v[182:185], v[98:101]
	v_mfma_f32_16x16x32_bf16 v[86:89], v[230:233], v[208:211], v[86:89]
	v_mfma_f32_16x16x32_bf16 v[82:85], v[238:241], v[208:211], v[82:85]
	v_mfma_f32_16x16x32_bf16 v[70:73], v[230:233], v[216:219], v[70:73]
	v_mfma_f32_16x16x32_bf16 v[66:69], v[238:241], v[216:219], v[66:69]
	s_mov_b32 m0, s92
	s_add_u32 s98, s48, s26
	s_addc_u32 s99, s49, s27
	s_barrier
	ds_read_b128 v[170:173], v168 offset:16384
	ds_read_b128 v[174:177], v168 offset:17408
	ds_read_b128 v[178:181], v168 offset:18432
	ds_read_b128 v[182:185], v168 offset:19456
	ds_read_b128 v[204:207], v168 offset:20480
	ds_read_b128 v[208:211], v168 offset:21504
	ds_read_b128 v[212:215], v168 offset:22528
	ds_read_b128 v[216:219], v168 offset:23552
	global_load_lds_dwordx4 v142, s[48:49]
	s_mov_b32 m0, s93
	s_nop 0
	global_load_lds_dwordx4 v140, s[48:49]
	s_barrier
	s_waitcnt lgkmcnt(0)
	s_waitcnt lgkmcnt(0)
	v_mfma_f32_16x16x32_bf16 v[62:65], v[130:133], v[170:173], v[62:65]
	v_mfma_f32_16x16x32_bf16 v[58:61], v[148:151], v[170:173], v[58:61]
	v_mfma_f32_16x16x32_bf16 v[46:49], v[130:133], v[178:181], v[46:49]
	v_mfma_f32_16x16x32_bf16 v[42:45], v[148:151], v[178:181], v[42:45]
	v_mfma_f32_16x16x32_bf16 v[30:33], v[130:133], v[204:207], v[30:33]
	v_mfma_f32_16x16x32_bf16 v[26:29], v[148:151], v[204:207], v[26:29]
	v_mfma_f32_16x16x32_bf16 v[14:17], v[130:133], v[212:215], v[14:17]
	v_mfma_f32_16x16x32_bf16 v[10:13], v[148:151], v[212:215], v[10:13]
	v_mfma_f32_16x16x32_bf16 v[62:65], v[134:137], v[174:177], v[62:65]
	v_mfma_f32_16x16x32_bf16 v[58:61], v[152:155], v[174:177], v[58:61]
	v_mfma_f32_16x16x32_bf16 v[46:49], v[134:137], v[182:185], v[46:49]
	v_mfma_f32_16x16x32_bf16 v[42:45], v[152:155], v[182:185], v[42:45]
	v_mfma_f32_16x16x32_bf16 v[30:33], v[134:137], v[208:211], v[30:33]
	v_mfma_f32_16x16x32_bf16 v[26:29], v[152:155], v[208:211], v[26:29]
	v_mfma_f32_16x16x32_bf16 v[14:17], v[134:137], v[216:219], v[14:17]
	v_mfma_f32_16x16x32_bf16 v[10:13], v[152:155], v[216:219], v[10:13]
	s_barrier
	s_add_u32 s60, s6, 0x100000
	s_addc_u32 s61, s7, 0
	s_add_i32 s5, s5, s91
	s_mov_b32 m0, s5
	s_nop 0
	global_load_lds_dwordx4 v0, s[60:61]
	s_add_i32 m0, s5, 0x2000
	s_nop 0
	global_load_lds_dwordx4 v138, s[60:61]
	s_waitcnt vmcnt(6)
	s_barrier
; #define PG8_STAGE(bufoff, gbase, voff) do { _Pragma("unroll") for (int _i = 0; _i < 2; ++_i) \
;         __builtin_amdgcn_global_load_lds((const unsigned*)((const char*)(gbase) + (voff)[_i]), (LAS unsigned*)(lds + (bufoff) + ldsw + _i * 8192), 16, 0, 0); } while (0)
; #define PG8_LDA(dst, b, h) do { _Pragma("unroll") for (int m = 0; m < 4; ++m) _Pragma("unroll") for (int k = 0; k < 2; ++k) dst[m][k] = *(const LAS bf16x8*)(lds + PG8_SA(b, h) + aoff + m * 2048 + k * 1024); } while (0)
; #define PG8_LDB(dst, b, h) do { _Pragma("unroll") for (int n = 0; n < 2; ++n) _Pragma("unroll") for (int k = 0; k < 2; ++k) dst[n][k] = *(const LAS bf16x8*)(lds + PG8_SB(b, h) + boff + n * 2048 + k * 1024); } while (0)
; #define PG8_WAIT_V(n) asm volatile("s_waitcnt vmcnt(" #n ")" ::: "memory")
; #define PG8_WAIT_L(n) asm volatile("s_waitcnt lgkmcnt(" #n ")" ::: "memory")
; #define PG8_BAR __builtin_amdgcn_s_barrier()
; #define PG8_SCHED __builtin_amdgcn_sched_barrier(0)
; template <class Epi>
; __device__ __forceinline__ void gemm_phase(LAS unsigned char* lds, const Gemm g, const StaticOrder& S, const Epi& E) {
;     ...
;             PG8_LDB(B0, 0, 0); PG8_SCHED; PG8_LDA(At, 0, 0); PG8_STAGE(PG8_SA(1, 1), a1 + hstep, voffA);
;             PG8_WAIT_L(8); PG8_BAR; PG8_WAIT_L(0); PG8_MMA(0, 0, At, B0); PG8_BAR; PG8_SCHED;
;             PG8_LDB(B1, 0, 1); PG8_STAGE(PG8_SB(0, 0), b2, voffB);
;             PG8_BAR; PG8_WAIT_L(0); PG8_MMA(0, 1, At, B1); PG8_BAR;
;             PG8_LDA(At, 0, 1); PG8_STAGE(PG8_SA(0, 0), a2, voffA);
;             PG8_BAR; PG8_WAIT_L(0); PG8_MMA(1, 0, At, B0); PG8_BAR; PG8_SCHED;
;             PG8_STAGE(PG8_SB(0, 1), b2 + hstep, voffB);
;             PG8_WAIT_V(6); PG8_BAR; PG8_MMA(1, 1, At, B1); PG8_BAR;
;             PG8_LDB(B0, 1, 0); PG8_SCHED; PG8_LDA(At, 1, 0); PG8_STAGE(PG8_SA(0, 1), a2 + hstep, voffA);
;             PG8_WAIT_L(8); PG8_BAR; PG8_WAIT_L(0); PG8_MMA(0, 0, At, B0); PG8_BAR; PG8_SCHED;
;             PG8_LDB(B1, 1, 1); PG8_STAGE(PG8_SB(1, 0), b3, voffB);
;             PG8_BAR; PG8_WAIT_L(0); PG8_MMA(0, 1, At, B1); PG8_BAR;
;             PG8_LDA(At, 1, 1); PG8_STAGE(PG8_SA(1, 0), a3, voffA);
;             PG8_BAR; PG8_WAIT_L(0); PG8_MMA(1, 0, At, B0); PG8_BAR; PG8_SCHED;
;             PG8_STAGE(PG8_SB(1, 1), b3 + hstep, voffB);
;             PG8_WAIT_V(6); PG8_BAR; PG8_MMA(1, 1, At, B1); PG8_BAR;
	v_mfma_f32_16x16x32_bf16 v[54:57], v[226:229], v[170:173], v[54:57]
	v_mfma_f32_16x16x32_bf16 v[50:53], v[234:237], v[170:173], v[50:53]
	v_mfma_f32_16x16x32_bf16 v[38:41], v[226:229], v[178:181], v[38:41]
	v_mfma_f32_16x16x32_bf16 v[34:37], v[234:237], v[178:181], v[34:37]
	v_mfma_f32_16x16x32_bf16 v[22:25], v[226:229], v[204:207], v[22:25]
	v_mfma_f32_16x16x32_bf16 v[18:21], v[234:237], v[204:207], v[18:21]
	v_mfma_f32_16x16x32_bf16 v[6:9], v[226:229], v[212:215], v[6:9]
	v_mfma_f32_16x16x32_bf16 v[2:5], v[234:237], v[212:215], v[2:5]
	v_mfma_f32_16x16x32_bf16 v[54:57], v[230:233], v[174:177], v[54:57]
	v_mfma_f32_16x16x32_bf16 v[50:53], v[238:241], v[174:177], v[50:53]
	v_mfma_f32_16x16x32_bf16 v[38:41], v[230:233], v[182:185], v[38:41]
	v_mfma_f32_16x16x32_bf16 v[34:37], v[238:241], v[182:185], v[34:37]
	v_mfma_f32_16x16x32_bf16 v[22:25], v[230:233], v[208:211], v[22:25]
	v_mfma_f32_16x16x32_bf16 v[18:21], v[238:241], v[208:211], v[18:21]
	v_mfma_f32_16x16x32_bf16 v[6:9], v[230:233], v[216:219], v[6:9]
	v_mfma_f32_16x16x32_bf16 v[2:5], v[238:241], v[216:219], v[2:5]
	s_add_i32 s5, 0, 0x18000
	v_add_u32_e32 v152, s5, v157
	s_barrier
	ds_read_b128 v[130:133], v152
	ds_read_b128 v[134:137], v152 offset:1024
	ds_read_b128 v[148:151], v152 offset:2048
	ds_read_b128 v[152:155], v152 offset:3072
	s_add_u32 s48, s48, 0x100000
	s_addc_u32 s49, s49, 0
	s_mov_b32 m0, s96
	ds_read_b128 v[170:173], v168 offset:32768
	ds_read_b128 v[174:177], v168 offset:33792
	ds_read_b128 v[178:181], v168 offset:34816
	ds_read_b128 v[182:185], v168 offset:35840
	ds_read_b128 v[204:207], v168 offset:36864
	ds_read_b128 v[208:211], v168 offset:37888
	ds_read_b128 v[212:215], v168 offset:38912
	ds_read_b128 v[216:219], v168 offset:39936
	global_load_lds_dwordx4 v142, s[48:49]
	s_mov_b32 m0, s97
	s_nop 0
	global_load_lds_dwordx4 v140, s[48:49]
	s_waitcnt lgkmcnt(8)
	s_barrier
	s_waitcnt lgkmcnt(0)
	s_waitcnt lgkmcnt(0)
	v_mfma_f32_16x16x32_bf16 v[126:129], v[130:133], v[170:173], v[126:129]
	v_mfma_f32_16x16x32_bf16 v[122:125], v[148:151], v[170:173], v[122:125]
	v_mfma_f32_16x16x32_bf16 v[110:113], v[130:133], v[178:181], v[110:113]
	v_mfma_f32_16x16x32_bf16 v[106:109], v[148:151], v[178:181], v[106:109]
	v_mfma_f32_16x16x32_bf16 v[94:97], v[130:133], v[204:207], v[94:97]
	v_mfma_f32_16x16x32_bf16 v[90:93], v[148:151], v[204:207], v[90:93]
	v_mfma_f32_16x16x32_bf16 v[78:81], v[130:133], v[212:215], v[78:81]
	v_mfma_f32_16x16x32_bf16 v[74:77], v[148:151], v[212:215], v[74:77]
	v_mfma_f32_16x16x32_bf16 v[126:129], v[134:137], v[174:177], v[126:129]
	v_mfma_f32_16x16x32_bf16 v[122:125], v[152:155], v[174:177], v[122:125]
	v_mfma_f32_16x16x32_bf16 v[110:113], v[134:137], v[182:185], v[110:113]
	v_mfma_f32_16x16x32_bf16 v[106:109], v[152:155], v[182:185], v[106:109]
	v_mfma_f32_16x16x32_bf16 v[94:97], v[134:137], v[208:211], v[94:97]
	v_mfma_f32_16x16x32_bf16 v[90:93], v[152:155], v[208:211], v[90:93]
	v_mfma_f32_16x16x32_bf16 v[78:81], v[134:137], v[216:219], v[78:81]
	v_mfma_f32_16x16x32_bf16 v[74:77], v[152:155], v[216:219], v[74:77]
	s_barrier
	s_add_i32 s48, 0, 0x1c000
	s_add_i32 s5, s5, s91
	v_add_u32_e32 v169, s48, v157
	s_mov_b32 m0, s5
	ds_read_b128 v[226:229], v169
	ds_read_b128 v[230:233], v169 offset:1024
	ds_read_b128 v[234:237], v169 offset:2048
	ds_read_b128 v[238:241], v169 offset:3072
	global_load_lds_dwordx4 v0, s[100:101]
	s_add_i32 m0, s5, 0x2000
	s_nop 0
	global_load_lds_dwordx4 v138, s[100:101]
	s_barrier
	s_waitcnt lgkmcnt(0)
	s_waitcnt lgkmcnt(0)
	v_mfma_f32_16x16x32_bf16 v[118:121], v[226:229], v[170:173], v[118:121]
	v_mfma_f32_16x16x32_bf16 v[114:117], v[234:237], v[170:173], v[114:117]
	v_mfma_f32_16x16x32_bf16 v[102:105], v[226:229], v[178:181], v[102:105]
	v_mfma_f32_16x16x32_bf16 v[98:101], v[234:237], v[178:181], v[98:101]
	v_mfma_f32_16x16x32_bf16 v[86:89], v[226:229], v[204:207], v[86:89]
	v_mfma_f32_16x16x32_bf16 v[82:85], v[234:237], v[204:207], v[82:85]
	v_mfma_f32_16x16x32_bf16 v[70:73], v[226:229], v[212:215], v[70:73]
	v_mfma_f32_16x16x32_bf16 v[66:69], v[234:237], v[212:215], v[66:69]
	v_mfma_f32_16x16x32_bf16 v[118:121], v[230:233], v[174:177], v[118:121]
	v_mfma_f32_16x16x32_bf16 v[114:117], v[238:241], v[174:177], v[114:117]
	v_mfma_f32_16x16x32_bf16 v[102:105], v[230:233], v[182:185], v[102:105]
	v_mfma_f32_16x16x32_bf16 v[98:101], v[238:241], v[182:185], v[98:101]
	v_mfma_f32_16x16x32_bf16 v[86:89], v[230:233], v[208:211], v[86:89]
	v_mfma_f32_16x16x32_bf16 v[82:85], v[238:241], v[208:211], v[82:85]
	v_mfma_f32_16x16x32_bf16 v[70:73], v[230:233], v[216:219], v[70:73]
	v_mfma_f32_16x16x32_bf16 v[66:69], v[238:241], v[216:219], v[66:69]
	s_mov_b32 m0, s54
	s_barrier
	ds_read_b128 v[170:173], v168 offset:49152
	ds_read_b128 v[174:177], v168 offset:50176
	ds_read_b128 v[178:181], v168 offset:51200
	ds_read_b128 v[182:185], v168 offset:52224
	ds_read_b128 v[204:207], v168 offset:53248
	ds_read_b128 v[208:211], v168 offset:54272
	ds_read_b128 v[212:215], v168 offset:55296
	ds_read_b128 v[216:219], v168 offset:56320
	global_load_lds_dwordx4 v142, s[98:99]
	s_mov_b32 m0, s84
	s_nop 0
	global_load_lds_dwordx4 v140, s[98:99]
	s_barrier
; #define PG8_STAGE(bufoff, gbase, voff) do { _Pragma("unroll") for (int _i = 0; _i < 2; ++_i) \
;         __builtin_amdgcn_global_load_lds((const unsigned*)((const char*)(gbase) + (voff)[_i]), (LAS unsigned*)(lds + (bufoff) + ldsw + _i * 8192), 16, 0, 0); } while (0)
; #define PG8_LDA(dst, b, h) do { _Pragma("unroll") for (int m = 0; m < 4; ++m) _Pragma("unroll") for (int k = 0; k < 2; ++k) dst[m][k] = *(const LAS bf16x8*)(lds + PG8_SA(b, h) + aoff + m * 2048 + k * 1024); } while (0)
; #define PG8_LDB(dst, b, h) do { _Pragma("unroll") for (int n = 0; n < 2; ++n) _Pragma("unroll") for (int k = 0; k < 2; ++k) dst[n][k] = *(const LAS bf16x8*)(lds + PG8_SB(b, h) + boff + n * 2048 + k * 1024); } while (0)
; #define PG8_WAIT_V(n) asm volatile("s_waitcnt vmcnt(" #n ")" ::: "memory")
; #define PG8_WAIT_L(n) asm volatile("s_waitcnt lgkmcnt(" #n ")" ::: "memory")
; #define PG8_BAR __builtin_amdgcn_s_barrier()
; #define PG8_SCHED __builtin_amdgcn_sched_barrier(0)
; template <class Epi>
; __device__ __forceinline__ void gemm_phase(LAS unsigned char* lds, const Gemm g, const StaticOrder& S, const Epi& E) {
;     ...
;             PG8_LDB(B0, 0, 0); PG8_SCHED; PG8_LDA(At, 0, 0); PG8_STAGE(PG8_SA(1, 1), a1 + hstep, voffA);
;             PG8_WAIT_L(8); PG8_BAR; PG8_WAIT_L(0); PG8_MMA(0, 0, At, B0); PG8_BAR; PG8_SCHED;
;             PG8_LDB(B1, 0, 1); PG8_STAGE(PG8_SB(0, 0), b2, voffB);
;             PG8_BAR; PG8_WAIT_L(0); PG8_MMA(0, 1, At, B1); PG8_BAR;
;             PG8_LDA(At, 0, 1); PG8_STAGE(PG8_SA(0, 0), a2, voffA);
;             PG8_BAR; PG8_WAIT_L(0); PG8_MMA(1, 0, At, B0); PG8_BAR; PG8_SCHED;
;             PG8_STAGE(PG8_SB(0, 1), b2 + hstep, voffB);
;             PG8_WAIT_V(6); PG8_BAR; PG8_MMA(1, 1, At, B1); PG8_BAR;
;             PG8_LDB(B0, 1, 0); PG8_SCHED; PG8_LDA(At, 1, 0); PG8_STAGE(PG8_SA(0, 1), a2 + hstep, voffA);
;             PG8_WAIT_L(8); PG8_BAR; PG8_WAIT_L(0); PG8_MMA(0, 0, At, B0); PG8_BAR; PG8_SCHED;
;             PG8_LDB(B1, 1, 1); PG8_STAGE(PG8_SB(1, 0), b3, voffB);
;             PG8_BAR; PG8_WAIT_L(0); PG8_MMA(0, 1, At, B1); PG8_BAR;
;             PG8_LDA(At, 1, 1); PG8_STAGE(PG8_SA(1, 0), a3, voffA);
;             PG8_BAR; PG8_WAIT_L(0); PG8_MMA(1, 0, At, B0); PG8_BAR; PG8_SCHED;
;             PG8_STAGE(PG8_SB(1, 1), b3 + hstep, voffB);
;             PG8_WAIT_V(6); PG8_BAR; PG8_MMA(1, 1, At, B1); PG8_BAR;
	s_waitcnt lgkmcnt(0)
	s_waitcnt lgkmcnt(0)
	v_mfma_f32_16x16x32_bf16 v[62:65], v[130:133], v[170:173], v[62:65]
	v_mfma_f32_16x16x32_bf16 v[58:61], v[148:151], v[170:173], v[58:61]
	v_mfma_f32_16x16x32_bf16 v[46:49], v[130:133], v[178:181], v[46:49]
	v_mfma_f32_16x16x32_bf16 v[42:45], v[148:151], v[178:181], v[42:45]
	v_mfma_f32_16x16x32_bf16 v[30:33], v[130:133], v[204:207], v[30:33]
	v_mfma_f32_16x16x32_bf16 v[26:29], v[148:151], v[204:207], v[26:29]
	v_mfma_f32_16x16x32_bf16 v[14:17], v[130:133], v[212:215], v[14:17]
	v_mfma_f32_16x16x32_bf16 v[10:13], v[148:151], v[212:215], v[10:13]
	v_mfma_f32_16x16x32_bf16 v[62:65], v[134:137], v[174:177], v[62:65]
	v_mfma_f32_16x16x32_bf16 v[58:61], v[152:155], v[174:177], v[58:61]
	v_mfma_f32_16x16x32_bf16 v[46:49], v[134:137], v[182:185], v[46:49]
	v_mfma_f32_16x16x32_bf16 v[42:45], v[152:155], v[182:185], v[42:45]
	v_mfma_f32_16x16x32_bf16 v[30:33], v[134:137], v[208:211], v[30:33]
	v_mfma_f32_16x16x32_bf16 v[26:29], v[152:155], v[208:211], v[26:29]
	v_mfma_f32_16x16x32_bf16 v[14:17], v[134:137], v[216:219], v[14:17]
	v_mfma_f32_16x16x32_bf16 v[10:13], v[152:155], v[216:219], v[10:13]
	s_barrier
	s_add_u32 s6, s6, 0x100080
	s_addc_u32 s7, s7, 0
	s_add_i32 s5, s48, s91
	s_mov_b32 m0, s5
	s_nop 0
	global_load_lds_dwordx4 v0, s[6:7]
	s_add_i32 m0, s5, 0x2000
	s_nop 0
	global_load_lds_dwordx4 v138, s[6:7]
	s_waitcnt vmcnt(6)
	s_barrier
	v_mfma_f32_16x16x32_bf16 v[54:57], v[226:229], v[170:173], v[54:57]
	v_mfma_f32_16x16x32_bf16 v[50:53], v[234:237], v[170:173], v[50:53]
	v_mfma_f32_16x16x32_bf16 v[38:41], v[226:229], v[178:181], v[38:41]
	v_mfma_f32_16x16x32_bf16 v[34:37], v[234:237], v[178:181], v[34:37]
	v_mfma_f32_16x16x32_bf16 v[22:25], v[226:229], v[204:207], v[22:25]
	v_mfma_f32_16x16x32_bf16 v[18:21], v[234:237], v[204:207], v[18:21]
	v_mfma_f32_16x16x32_bf16 v[6:9], v[226:229], v[212:215], v[6:9]
	v_mfma_f32_16x16x32_bf16 v[2:5], v[234:237], v[212:215], v[2:5]
	v_mfma_f32_16x16x32_bf16 v[54:57], v[230:233], v[174:177], v[54:57]
	v_mfma_f32_16x16x32_bf16 v[50:53], v[238:241], v[174:177], v[50:53]
	v_mfma_f32_16x16x32_bf16 v[38:41], v[230:233], v[182:185], v[38:41]
	v_mfma_f32_16x16x32_bf16 v[34:37], v[238:241], v[182:185], v[34:37]
	v_mfma_f32_16x16x32_bf16 v[22:25], v[230:233], v[208:211], v[22:25]
	v_mfma_f32_16x16x32_bf16 v[18:21], v[238:241], v[208:211], v[18:21]
	v_mfma_f32_16x16x32_bf16 v[6:9], v[230:233], v[216:219], v[6:9]
	v_mfma_f32_16x16x32_bf16 v[2:5], v[238:241], v[216:219], v[2:5]
	s_add_i32 s4, s4, 2
	s_add_u32 s46, s46, 0x100
	s_addc_u32 s47, s47, 0
	s_add_u32 vcc_lo, vcc_lo, 0x100
	s_addc_u32 vcc_hi, vcc_hi, 0
	s_cmp_gt_u32 s4, 61
	s_barrier
	s_cbranch_scc0 .LBB0_103
; __device__ __forceinline__ unsigned pk2(float lo, float hi) { unsigned r; asm("v_cvt_pk_bf16_f32 %0, %1, %2" : "=v"(r) : "v"(lo), "v"(hi)); return r; }
; __device__ __forceinline__ float bf_lo(unsigned w) { return __uint_as_float(w << 16); }
; __device__ __forceinline__ float bf_hi(unsigned w) { return __uint_as_float(w & 0xffff0000u); }
;     __device__ __forceinline__ void operator()(const f32x4 (&acc)[2][2][4][2], const Unit& u, int  , int wr, int wc, int fr, int fq) const {
;         const int row0 = u.pm * BM + wr * 64 + fr, col0 = u.pn * BM + wc * 32 + 8 * fq;
;         u32x4 rv[2][2];
; #pragma unroll
;         for (int bj = 0; bj < 2; ++bj) rv[0][bj] = *(const u32x4*)(hb + (size_t)row0 * DM + col0 + bj * HALF);
; #pragma unroll
;         for (int g = 0; g < 8; ++g) {
;             const int ai = g >> 2, m = g & 3;
;             const int row = row0 + ai * HALF + m * 16; const size_t off = (size_t)row * DM + col0; float s = 0.f;
;             if (g < 7) { const int g1 = g + 1; const size_t off1 = (size_t)(row0 + (g1 >> 2) * HALF + (g1 & 3) * 16) * DM + col0;
; #pragma unroll
;                 for (int bj = 0; bj < 2; ++bj) rv[g1 & 1][bj] = *(const u32x4*)(hb + off1 + bj * HALF); }
; #pragma unroll
;             for (int bj = 0; bj < 2; ++bj) {
;                 const u32x4 r = rv[g & 1][bj]; const f32x4 a0 = acc[ai][bj][m][0], a1 = acc[ai][bj][m][1];
;                 u32x4 o; o.x = pk2(bf_lo(r.x) + a0[0], bf_hi(r.x) + a0[1]); o.y = pk2(bf_lo(r.y) + a0[2], bf_hi(r.y) + a0[3]);
;                 o.z = pk2(bf_lo(r.z) + a1[0], bf_hi(r.z) + a1[1]); o.w = pk2(bf_lo(r.w) + a1[2], bf_hi(r.w) + a1[3]);
;                 *(u32x4*)(hb + off + bj * HALF) = o;
; #pragma unroll
;                 for (int e = 0; e < 4; ++e) { const float x0 = bf_lo(o[e]), x1 = bf_hi(o[e]); s += x0 * x0 + x1 * x1; }
;             }
;             s += __shfl_xor(s, 16); s += __shfl_xor(s, 32);
;             if (fq == 0) ssq[(size_t)row * 16 + u.pn * 4 + wc] = s;
	v_lshl_add_u32 v150, s86, 8, v156
	v_lshl_or_b32 v148, s18, 8, v166
	v_ashrrev_i32_e32 v151, 31, v150
	v_lshlrev_b64 v[130:131], 11, v[150:151]
	v_ashrrev_i32_e32 v149, 31, v148
	v_lshl_add_u64 v[130:131], s[8:9], 0, v[130:131]
	v_lshlrev_b64 v[132:133], 1, v[148:149]
	v_lshl_add_u64 v[162:163], v[130:131], 0, v[132:133]
	global_load_dwordx4 v[170:173], v[162:163], off
	global_load_dwordx4 v[174:177], v[162:163], off offset:256
	v_or_b32_e32 v152, 16, v150
	v_ashrrev_i32_e32 v153, 31, v152
	v_lshlrev_b64 v[130:131], 11, v[152:153]
	v_lshl_add_u64 v[130:131], s[8:9], 0, v[130:131]
	v_lshl_add_u64 v[154:155], v[130:131], 0, v[132:133]
	global_load_dwordx4 v[134:137], v[154:155], off
	global_load_dwordx4 v[130:133], v[154:155], off offset:256
	v_lshlrev_b32_e32 v202, 11, v150
	v_lshl_add_u32 v202, v148, 1, v202
	v_add_u32_e32 v202, 0x10000, v202
	global_load_dwordx4 v[204:207], v202, s[8:9]
	global_load_dwordx4 v[208:211], v202, s[8:9] offset:256
	v_add_u32_e32 v202, 0x8000, v202
	global_load_dwordx4 v[212:215], v202, s[8:9]
	global_load_dwordx4 v[216:219], v202, s[8:9] offset:256
	v_add_u32_e32 v202, 0x28000, v202
	global_load_dwordx4 v[226:229], v202, s[8:9]
	global_load_dwordx4 v[230:233], v202, s[8:9] offset:256
	v_add_u32_e32 v202, 0x8000, v202
	global_load_dwordx4 v[234:237], v202, s[8:9]
	global_load_dwordx4 v[238:241], v202, s[8:9] offset:256
	v_add_u32_e32 v202, 0x8000, v202
	global_load_dwordx4 v[158:161], v202, s[8:9]
	global_load_dwordx4 v[188:191], v202, s[8:9] offset:256
	v_add_u32_e32 v202, 0x8000, v202
	global_load_dwordx4 v[194:197], v202, s[8:9]
	global_load_dwordx4 v[198:201], v202, s[8:9] offset:256
	v_and_b32_e32 v178, 64, v193
	v_xor_b32_e32 v169, 16, v193
	s_lshl_b32 s6, s18, 2
	s_ashr_i32 s7, s6, 31
	s_waitcnt vmcnt(12)
	v_lshlrev_b32_e32 v181, 16, v172
	v_lshlrev_b32_e32 v182, 16, v173
	v_and_b32_e32 v173, 0xffff0000, v173
	v_lshlrev_b32_e32 v185, 16, v176
	v_and_b32_e32 v176, 0xffff0000, v176
	v_lshlrev_b32_e32 v179, 16, v170
	v_and_b32_e32 v170, 0xffff0000, v170
	v_lshlrev_b32_e32 v180, 16, v171
	v_and_b32_e32 v171, 0xffff0000, v171
	v_and_b32_e32 v172, 0xffff0000, v172
	v_lshlrev_b32_e32 v183, 16, v174
	v_and_b32_e32 v174, 0xffff0000, v174
	v_lshlrev_b32_e32 v186, 16, v177
	v_and_b32_e32 v177, 0xffff0000, v177
	v_add_f32_e32 v122, v122, v181
	v_add_f32_e32 v125, v125, v173
	v_add_f32_e32 v115, v115, v176
	v_add_f32_e32 v126, v126, v179
	v_add_f32_e32 v127, v127, v170
	v_add_f32_e32 v128, v128, v180
	v_add_f32_e32 v129, v129, v171
	v_add_f32_e32 v123, v123, v172
	v_add_f32_e32 v124, v124, v182
	v_add_f32_e32 v170, v118, v183
	v_add_f32_e32 v171, v119, v174
	v_add_f32_e32 v114, v114, v185
	v_add_f32_e32 v173, v116, v186
	v_add_f32_e32 v174, v117, v177
	v_cvt_pk_bf16_f32 v116, v126, v127
	v_cvt_pk_bf16_f32 v117, v128, v129
	v_cvt_pk_bf16_f32 v118, v122, v123
	v_cvt_pk_bf16_f32 v119, v124, v125
	v_cvt_pk_bf16_f32 v122, v114, v115
	v_lshlrev_b32_e32 v184, 16, v175
	v_and_b32_e32 v115, 0xffff0000, v116
	v_and_b32_e32 v125, 0xffff0000, v117
	v_lshlrev_b32_e32 v114, 16, v116
	v_lshlrev_b32_e32 v124, 16, v117
	v_and_b32_e32 v127, 0xffff0000, v118
	v_mul_f32_e32 v115, v115, v115
	v_mul_f32_e32 v125, v125, v125
	v_and_b32_e32 v175, 0xffff0000, v175
	v_lshlrev_b32_e32 v126, 16, v118
	v_and_b32_e32 v129, 0xffff0000, v119
	v_mul_f32_e32 v127, v127, v127
	v_fmac_f32_e32 v115, v114, v114
	v_fmac_f32_e32 v125, v124, v124
	v_add_f32_e32 v172, v120, v184
	v_add_f32_e32 v121, v121, v175
	v_cvt_pk_bf16_f32 v120, v170, v171
	v_lshlrev_b32_e32 v128, 16, v119
	v_and_b32_e32 v171, 0xffff0000, v120
	v_mul_f32_e32 v129, v129, v129
	v_fmac_f32_e32 v127, v126, v126
	v_add_f32_e32 v114, v115, v125
	v_cvt_pk_bf16_f32 v121, v172, v121
	v_cvt_pk_bf16_f32 v123, v173, v174
	v_lshlrev_b32_e32 v170, 16, v120
	v_and_b32_e32 v173, 0xffff0000, v121
	v_mul_f32_e32 v171, v171, v171
	v_fmac_f32_e32 v129, v128, v128
	v_add_f32_e32 v114, v114, v127
	v_lshlrev_b32_e32 v172, 16, v121
	v_and_b32_e32 v175, 0xffff0000, v122
	v_mul_f32_e32 v173, v173, v173
	v_fmac_f32_e32 v171, v170, v170
	v_add_f32_e32 v114, v114, v129
	v_lshlrev_b32_e32 v174, 16, v122
	v_and_b32_e32 v177, 0xffff0000, v123
	v_mul_f32_e32 v175, v175, v175
	v_fmac_f32_e32 v173, v172, v172
	v_add_f32_e32 v114, v114, v171
	v_add_u32_e32 v115, 64, v178
	v_lshlrev_b32_e32 v176, 16, v123
	v_mul_f32_e32 v177, v177, v177
	v_fmac_f32_e32 v175, v174, v174
	v_add_f32_e32 v114, v114, v173
	v_cmp_lt_i32_e32 vcc, v169, v115
	v_fmac_f32_e32 v177, v176, v176
	v_add_f32_e32 v114, v114, v175
	v_cndmask_b32_e32 v124, v193, v169, vcc
	v_add_f32_e32 v114, v114, v177
	v_lshlrev_b32_e32 v126, 2, v124
	ds_bpermute_b32 v124, v126, v114
	global_store_dwordx4 v[162:163], v[116:119], off
	global_store_dwordx4 v[162:163], v[120:123], off offset:256
	s_waitcnt lgkmcnt(0)
	v_add_f32_e32 v114, v114, v124
	v_xor_b32_e32 v124, 32, v193
	v_cmp_lt_i32_e32 vcc, v124, v115
	s_nop 1
	v_cndmask_b32_e32 v115, v193, v124, vcc
	v_lshlrev_b32_e32 v127, 2, v115
	ds_bpermute_b32 v115, v127, v114
	s_and_saveexec_b64 s[46:47], s[40:41]
	s_cbranch_execz .LBB0_106
	s_waitcnt lgkmcnt(0)
	v_add_f32_e32 v116, v114, v115
	v_lshlrev_b64 v[114:115], 6, v[150:151]
	v_lshl_add_u64 v[114:115], s[10:11], 0, v[114:115]
	v_lshl_add_u64 v[114:115], s[6:7], 2, v[114:115]
	s_lshl_b32 s18, s83, 2
	v_lshl_add_u64 v[114:115], v[114:115], 0, s[18:19]
	global_store_dword v[114:115], v116, off

; #define PG8_WAIT_V(n) asm volatile("s_waitcnt vmcnt(" #n ")" ::: "memory")
; #define PG8_BAR __builtin_amdgcn_s_barrier()
; template <class Epi>
; __device__ __forceinline__ void gemm_phase(LAS unsigned char* lds, const Gemm g, const StaticOrder& S, const Epi& E) {
;     ...
;     PG8_WAIT_V(0);
;     if (wr == 0) PG8_BAR;
;     PG8_BAR;
.LBB0_120:
	v_mov_b32_e32 v188, 1
	v_mov_b32_e32 v189, 0x358637bd
	v_mov_b32_e32 v190, 0x260
	v_mov_b32_e32 v191, 0x3c0881c4
	v_mov_b32_e32 v194, 0xf149f2ca
	v_mov_b32_e32 v195, 0xc0
	v_mov_b32_e32 v196, 0x70
	v_mov_b32_e32 v197, 0x71
	v_mov_b32_e32 v198, 5
	v_mov_b32_e32 v199, 2
	v_mov_b32_e32 v200, 3
	v_not_b32_e32 v201, 63
	v_not_b32_e32 v202, 31
	s_waitcnt vmcnt(0)
	s_cmpk_gt_u32 s70, 0xff
	v_readlane_b32 s70, v254, 40
	v_readlane_b32 s84, v254, 42
	v_readlane_b32 s71, v254, 41
	v_readlane_b32 s86, v254, 44
	v_readlane_b32 s87, v254, 45
	v_readlane_b32 s88, v252, 6
	v_readlane_b32 s85, v254, 43
	s_cbranch_scc1 .LBB0_122
	s_barrier
.LBB0_122:
	s_setprio 0
	v_readlane_b32 s84, v253, 0
	v_readlane_b32 s85, v253, 1
	s_barrier
.LBB0_123:
	s_mov_b64 s[6:7], 0

; #define PG8_STAGE(bufoff, gbase, voff) do { _Pragma("unroll") for (int _i = 0; _i < 2; ++_i) \
;         __builtin_amdgcn_global_load_lds((const unsigned*)((const char*)(gbase) + (voff)[_i]), (LAS unsigned*)(lds + (bufoff) + ldsw + _i * 8192), 16, 0, 0); } while (0)
; #define PG8_WAIT_V(n) asm volatile("s_waitcnt vmcnt(" #n ")" ::: "memory")
; #define PG8_BAR __builtin_amdgcn_s_barrier()
; template <class Epi>
; __device__ __forceinline__ void gemm_phase(LAS unsigned char* lds, const Gemm g, const StaticOrder& S, const Epi& E) {
;     int tid = threadIdx.x; asm volatile("" : "+v"(tid));
;     const int wid = __builtin_amdgcn_readfirstlane(tid >> 6), lane = tid & 63, wr = wid >> 2, wc = wid & 3, fr = lane & 15, fq = lane >> 4;
;     const int K = g.K, nt = K / BK;
;     unsigned voffA[2], voffB[2];
; #pragma unroll
;     for (int i = 0; i < 2; ++i) { int R, C; stage_rc(tid * 16 + i * 8192, R, C); const int Rb = Epi::PERM ? ((R & ~31) + perm32(R & 31)) : R;
;         voffA[i] = (unsigned)(R * K + C) * 2u; voffB[i] = (unsigned)(Rb * K + C) * 2u; }
;     const size_t kstep = (size_t)(BK * 2);
;     const size_t hstep = (size_t)HALF * K * 2;
;     const size_t tstep = 2 * hstep;
;     const unsigned ldsw = (unsigned)wid * 1024u;
;     const int aoff = lds_byte(wr * 64 + fr, fq * 8), boff = lds_byte(wc * 32 + fr, fq * 8);
;     ...
;     Unit cur, nxt; int ui = 0;
;     if (!S.next(0, cur)) return;
;     f32x4 acc[2][2][4][2];
; #pragma unroll
;     for (int a = 0; a < 2; ++a)
; #pragma unroll
;         for (int b = 0; b < 2; ++b)
; #pragma unroll
;             for (int m = 0; m < 4; ++m)
; #pragma unroll
;                 for (int n = 0; n < 2; ++n) acc[a][b][m][n] = (f32x4){0.f, 0.f, 0.f, 0.f};
;     bf16x8 At[4][2], B0[2][2], B1[2][2];
;     const char* cA = (const char*)g.A + (size_t)cur.pm * tstep; const char* cB = (const char*)g.Bt + (size_t)cur.pn * tstep;
;     PG8_STAGE(PG8_SB(0, 0), cB, voffB); PG8_STAGE(PG8_SA(0, 0), cA, voffA); PG8_STAGE(PG8_SB(0, 1), cB + hstep, voffB); PG8_STAGE(PG8_SA(0, 1), cA + hstep, voffA);
;     if (wr == 1) PG8_BAR;
;     PG8_WAIT_V(4); PG8_BAR;
;     PG8_STAGE(PG8_SB(1, 0), cB + kstep, voffB); PG8_STAGE(PG8_SA(1, 0), cA + kstep, voffA); PG8_STAGE(PG8_SB(1, 1), cB + hstep + kstep, voffB);
;     PG8_WAIT_V(6); PG8_BAR;
.LBB0_188:
	v_readlane_b32 s4, v253, 56
	v_mov_b32_e32 v0, v167
	v_readlane_b32 s5, v253, 57
	s_waitcnt vmcnt(0) lgkmcnt(0)
	s_barrier
	s_andn2_b64 vcc, exec, s[4:5]
	v_readfirstlane_b32 s4, v0
	s_cbranch_vccnz .LBB0_228
	v_lshlrev_b32_e32 v2, 4, v0
	v_add_u32_e32 v3, 0x2000, v2
	v_ashrrev_i32_e32 v4, 31, v3
	v_lshrrev_b32_e32 v4, 22, v4
	v_add_u32_e32 v4, v3, v4
	v_ashrrev_i32_e32 v10, 10, v4
	v_mul_i32_i24_e32 v4, 0x400, v10
	v_sub_u32_e32 v3, v3, v4
	v_lshrrev_b32_e32 v4, 4, v3
	v_writelane_b32 v252, s88, 6
	s_ashr_i32 s11, s4, 6
	v_bitop3_b32 v3, v4, v3, 32 bitop3:0x6c
	v_writelane_b32 v252, s4, 4
	s_ashr_i32 s10, s4, 8
	s_lshl_b32 s89, s11, 10
	s_lshl_b64 s[4:5], s[22:23], 21
	v_ashrrev_i32_e32 v4, 31, v3
	s_add_u32 s90, s94, 0x110b0000
	v_lshrrev_b32_e32 v4, 26, v4
	s_addc_u32 s91, s95, 0
	v_add_u32_e32 v4, v3, v4
	v_lshlrev_b32_e32 v5, 3, v10
	s_add_u32 s4, s94, s4
	v_ashrrev_i32_e32 v11, 6, v4
	v_and_b32_e32 v5, -16, v5
	s_addc_u32 s5, s95, s5
	v_add_u32_e32 v5, v11, v5
	s_add_u32 s92, s4, 0xe00000
	v_and_b32_e32 v6, 3, v11
	s_mov_b32 s4, 0x1fffe0
	v_lshrrev_b32_e32 v7, 2, v5
	v_lshlrev_b32_e32 v8, 1, v5
	v_and_b32_e32 v4, 0xc0, v4
	v_and_or_b32 v6, v5, s4, v6
	v_and_b32_e32 v7, 4, v7
	v_and_b32_e32 v8, 24, v8
	v_sub_u32_e32 v3, v3, v4
	v_or3_b32 v6, v6, v7, v8
	v_lshlrev_b32_e32 v7, 5, v10
	v_ashrrev_i16_sdwa v3, v188, sext(v3) dst_sel:DWORD dst_unused:UNUSED_PAD src0_sel:DWORD src1_sel:BYTE_0
	v_and_b32_e32 v7, 32, v7
	v_bfe_i32 v12, v3, 0, 16
	v_add_lshl_u32 v3, v7, v12, 1
	v_lshl_add_u32 v138, v6, 11, v3
	v_lshl_add_u32 v140, v5, 11, v3
	v_bfe_i32 v3, v0, 27, 1
	v_lshrrev_b32_e32 v3, 22, v3
	v_add_u32_e32 v3, v2, v3
	v_and_b32_e32 v3, 0xfffffc00, v3
	v_sub_u32_e32 v2, v2, v3
	v_lshrrev_b32_e32 v3, 4, v2
	v_ashrrev_i32_e32 v4, 31, v0
	v_bitop3_b32 v2, v3, v2, 32 bitop3:0x6c
	v_lshrrev_b32_e32 v4, 26, v4
	v_ashrrev_i32_e32 v3, 31, v2
	v_add_u32_e32 v4, v0, v4
	v_lshrrev_b32_e32 v3, 26, v3
	v_ashrrev_i32_e32 v14, 6, v4
	v_add_u32_e32 v3, v2, v3
	v_lshlrev_b32_e32 v4, 3, v14
	v_ashrrev_i32_e32 v13, 6, v3
	v_and_b32_e32 v4, -16, v4
	v_add_u32_e32 v4, v13, v4
	v_and_b32_e32 v5, 3, v13
	v_lshrrev_b32_e32 v6, 2, v4
	v_lshlrev_b32_e32 v7, 1, v4
	v_and_b32_e32 v3, 0xc0, v3
	v_and_or_b32 v5, v4, s4, v5
	v_and_b32_e32 v6, 4, v6
	v_and_b32_e32 v7, 24, v7
	v_sub_u32_e32 v2, v2, v3
	s_addc_u32 s93, s5, 0
	v_or3_b32 v5, v5, v6, v7
	v_lshlrev_b32_e32 v6, 5, v14
	v_ashrrev_i16_sdwa v2, v188, sext(v2) dst_sel:DWORD dst_unused:UNUSED_PAD src0_sel:DWORD src1_sel:BYTE_0
	v_readlane_b32 s4, v254, 11
	v_and_b32_e32 v6, 32, v6
	v_bfe_i32 v15, v2, 0, 16
	v_readlane_b32 s5, v254, 12
	s_add_u32 s6, s92, s4
	v_add_lshl_u32 v2, v6, v15, 1
	s_addc_u32 s7, s93, s5
	s_add_i32 s96, s89, 0
	v_lshl_add_u32 v142, v5, 11, v2
	s_add_i32 m0, s96, 0x10000
	v_readlane_b32 s4, v254, 36
	global_load_lds_dwordx4 v142, s[6:7]
	s_add_i32 m0, s96, 0x12000
	v_readlane_b32 s5, v254, 37
	s_add_u32 s44, s90, s4
	v_lshl_add_u32 v144, v4, 11, v2
	global_load_lds_dwordx4 v138, s[6:7]
	s_addc_u32 s45, s91, s5
	s_mov_b32 m0, s96
	s_add_i32 s97, s96, 0x2000
	global_load_lds_dwordx4 v144, s[44:45]
	s_mov_b32 m0, s97
	s_add_u32 s4, s6, 0x40000
	global_load_lds_dwordx4 v140, s[44:45]
	s_addc_u32 s5, s7, 0
	s_add_i32 m0, s96, 0x14000
	v_mov_b32_e32 v143, v1
	global_load_lds_dwordx4 v142, s[4:5]
	s_add_i32 m0, s96, 0x16000
	v_mov_b32_e32 v139, v1
	global_load_lds_dwordx4 v138, s[4:5]
	s_add_u32 s4, s44, 0x40000
	s_addc_u32 s5, s45, 0
	s_add_i32 s83, s96, 0x4000
	s_mov_b32 m0, s83
	s_add_i32 s88, s96, 0x6000
	global_load_lds_dwordx4 v144, s[4:5]
	s_mov_b32 m0, s88
	v_mov_b32_e32 v145, v1
	global_load_lds_dwordx4 v140, s[4:5]
	v_mov_b32_e32 v141, v1
	v_lshl_add_u64 v[8:9], s[6:7], 0, v[142:143]
	v_lshl_add_u64 v[6:7], s[6:7], 0, v[138:139]
	v_lshl_add_u64 v[4:5], s[44:45], 0, v[144:145]
	s_cmp_lg_u32 s10, 1
	v_lshl_add_u64 v[2:3], s[44:45], 0, v[140:141]
	s_cbranch_scc1 .LBB0_191
	s_barrier
	s_setprio 1

; #define PG8_STAGE(bufoff, gbase, voff) do { _Pragma("unroll") for (int _i = 0; _i < 2; ++_i) \
;         __builtin_amdgcn_global_load_lds((const unsigned*)((const char*)(gbase) + (voff)[_i]), (LAS unsigned*)(lds + (bufoff) + ldsw + _i * 8192), 16, 0, 0); } while (0)
; #define PG8_LDA(dst, b, h) do { _Pragma("unroll") for (int m = 0; m < 4; ++m) _Pragma("unroll") for (int k = 0; k < 2; ++k) dst[m][k] = *(const LAS bf16x8*)(lds + PG8_SA(b, h) + aoff + m * 2048 + k * 1024); } while (0)
; #define PG8_LDB(dst, b, h) do { _Pragma("unroll") for (int n = 0; n < 2; ++n) _Pragma("unroll") for (int k = 0; k < 2; ++k) dst[n][k] = *(const LAS bf16x8*)(lds + PG8_SB(b, h) + boff + n * 2048 + k * 1024); } while (0)
; #define PG8_MMA(ai, bj, At, Bt) do { __builtin_amdgcn_s_setprio(1); _Pragma("unroll") for (int m = 0; m < 4; ++m) _Pragma("unroll") for (int n = 0; n < 2; ++n) _Pragma("unroll") for (int k = 0; k < 2; ++k) \
;         acc[ai][bj][m][n] = __builtin_amdgcn_mfma_f32_16x16x32_bf16(Bt[n][k], At[m][k], acc[ai][bj][m][n], 0, 0, 0); __builtin_amdgcn_s_setprio(0); } while (0)
; #define PG8_WAIT_L(n) asm volatile("s_waitcnt lgkmcnt(" #n ")" ::: "memory")
; #define PG8_BAR __builtin_amdgcn_s_barrier()
; #define PG8_SCHED __builtin_amdgcn_sched_barrier(0)
; template <class Epi>
; __device__ __forceinline__ void gemm_phase(LAS unsigned char* lds, const Gemm g, const StaticOrder& S, const Epi& E) {
;     ...
;             const char* a1 = cA + (size_t)(t + 1) * kstep;
;             const char* a2 = last ? nA : cA + (size_t)(t + 2) * kstep; const char* b2 = last ? nB : cB + (size_t)(t + 2) * kstep;
;             const char* a3 = a2 + kstep; const char* b3 = b2 + kstep;
;             PG8_LDB(B0, 0, 0); PG8_SCHED; PG8_LDA(At, 0, 0); PG8_STAGE(PG8_SA(1, 1), a1 + hstep, voffA);
;             PG8_WAIT_L(8); PG8_BAR; PG8_WAIT_L(0); PG8_MMA(0, 0, At, B0); PG8_BAR; PG8_SCHED;
;             PG8_LDB(B1, 0, 1); PG8_STAGE(PG8_SB(0, 0), b2, voffB);
;             PG8_BAR; PG8_WAIT_L(0); PG8_MMA(0, 1, At, B1); PG8_BAR;
;             PG8_LDA(At, 0, 1); PG8_STAGE(PG8_SA(0, 0), a2, voffA);
;             PG8_BAR; PG8_WAIT_L(0); PG8_MMA(1, 0, At, B0); PG8_BAR; PG8_SCHED;
.LBB0_206:
	s_add_u32 s6, s44, s46
	s_addc_u32 s7, s45, s47
	s_add_u32 s6, s6, 0x100
	s_addc_u32 s7, s7, 0
	s_add_u32 s54, s60, s46
	s_addc_u32 s55, s61, s47
	s_add_i32 vcc_lo, 0, 0x10000
	v_add_u32_e32 v0, vcc_lo, v168
	ds_read_b128 v[150:153], v0
	ds_read_b128 v[154:157], v0 offset:1024
	ds_read_b128 v[172:175], v0 offset:2048
	ds_read_b128 v[176:179], v0 offset:3072
	s_cmpk_eq_i32 s46, 0x700
	s_cselect_b32 s48, s72, s6
	s_cselect_b32 s6, s58, s54
	s_cselect_b32 s49, s13, s7
	s_cselect_b32 s7, s11, s55
	v_lshl_add_u64 v[134:135], v[130:131], 0, s[46:47]
	s_add_i32 m0, s96, 0xc000
	ds_read_b128 v[180:183], v171
	ds_read_b128 v[184:187], v171 offset:1024
	ds_read_b128 v[204:207], v171 offset:2048
	ds_read_b128 v[208:211], v171 offset:3072
	ds_read_b128 v[212:215], v171 offset:4096
	ds_read_b128 v[216:219], v171 offset:5120
	ds_read_b128 v[226:229], v171 offset:6144
	ds_read_b128 v[230:233], v171 offset:7168
	global_load_lds_dwordx4 v[134:135], off
	v_lshl_add_u64 v[134:135], v[132:133], 0, s[46:47]
	s_add_i32 m0, s96, 0xe000
	s_nop 0
	global_load_lds_dwordx4 v[134:135], off
	s_waitcnt lgkmcnt(8)
	s_barrier
	s_waitcnt lgkmcnt(0)
	s_waitcnt lgkmcnt(0)
	v_mfma_f32_16x16x32_bf16 v[126:129], v[150:153], v[180:183], v[126:129]
	v_mfma_f32_16x16x32_bf16 v[122:125], v[172:175], v[180:183], v[122:125]
	v_mfma_f32_16x16x32_bf16 v[110:113], v[150:153], v[204:207], v[110:113]
	v_mfma_f32_16x16x32_bf16 v[106:109], v[172:175], v[204:207], v[106:109]
	v_mfma_f32_16x16x32_bf16 v[94:97], v[150:153], v[212:215], v[94:97]
	v_mfma_f32_16x16x32_bf16 v[90:93], v[172:175], v[212:215], v[90:93]
	v_mfma_f32_16x16x32_bf16 v[78:81], v[150:153], v[226:229], v[78:81]
	v_mfma_f32_16x16x32_bf16 v[74:77], v[172:175], v[226:229], v[74:77]
	v_mfma_f32_16x16x32_bf16 v[126:129], v[154:157], v[184:187], v[126:129]
	v_mfma_f32_16x16x32_bf16 v[122:125], v[176:179], v[184:187], v[122:125]
	v_mfma_f32_16x16x32_bf16 v[110:113], v[154:157], v[208:211], v[110:113]
	v_mfma_f32_16x16x32_bf16 v[106:109], v[176:179], v[208:211], v[106:109]
	v_mfma_f32_16x16x32_bf16 v[94:97], v[154:157], v[216:219], v[94:97]
	v_mfma_f32_16x16x32_bf16 v[90:93], v[176:179], v[216:219], v[90:93]
	v_mfma_f32_16x16x32_bf16 v[78:81], v[154:157], v[230:233], v[78:81]
	v_mfma_f32_16x16x32_bf16 v[74:77], v[176:179], v[230:233], v[74:77]
	s_barrier
	s_add_i32 vcc_hi, 0, 0x14000
	s_add_i32 s54, vcc_lo, s89
	v_add_u32_e32 v0, vcc_hi, v168
	v_lshl_add_u64 v[134:135], s[6:7], 0, v[142:143]
	s_mov_b32 m0, s54
	ds_read_b128 v[234:237], v0
	ds_read_b128 v[238:241], v0 offset:1024
	ds_read_b128 v[242:245], v0 offset:2048
	ds_read_b128 v[246:249], v0 offset:3072
	global_load_lds_dwordx4 v[134:135], off
	v_lshl_add_u64 v[220:221], s[6:7], 0, v[138:139]
	s_add_i32 m0, s54, 0x2000
	s_nop 0
	global_load_lds_dwordx4 v[220:221], off
	s_barrier
	s_waitcnt lgkmcnt(0)
	s_waitcnt lgkmcnt(0)
	v_mfma_f32_16x16x32_bf16 v[118:121], v[234:237], v[180:183], v[118:121]
	v_mfma_f32_16x16x32_bf16 v[114:117], v[242:245], v[180:183], v[114:117]
	v_mfma_f32_16x16x32_bf16 v[102:105], v[234:237], v[204:207], v[102:105]
	v_mfma_f32_16x16x32_bf16 v[98:101], v[242:245], v[204:207], v[98:101]
	v_mfma_f32_16x16x32_bf16 v[86:89], v[234:237], v[212:215], v[86:89]
	v_mfma_f32_16x16x32_bf16 v[82:85], v[242:245], v[212:215], v[82:85]
	v_mfma_f32_16x16x32_bf16 v[70:73], v[234:237], v[226:229], v[70:73]
	v_mfma_f32_16x16x32_bf16 v[66:69], v[242:245], v[226:229], v[66:69]
	v_mfma_f32_16x16x32_bf16 v[118:121], v[238:241], v[184:187], v[118:121]
	v_mfma_f32_16x16x32_bf16 v[114:117], v[246:249], v[184:187], v[114:117]
	v_mfma_f32_16x16x32_bf16 v[102:105], v[238:241], v[208:211], v[102:105]
	v_mfma_f32_16x16x32_bf16 v[98:101], v[246:249], v[208:211], v[98:101]
	v_mfma_f32_16x16x32_bf16 v[86:89], v[238:241], v[216:219], v[86:89]
	v_mfma_f32_16x16x32_bf16 v[82:85], v[246:249], v[216:219], v[82:85]
	v_mfma_f32_16x16x32_bf16 v[70:73], v[238:241], v[230:233], v[70:73]
	v_mfma_f32_16x16x32_bf16 v[66:69], v[246:249], v[230:233], v[66:69]
	s_mov_b32 m0, s96
	v_lshl_add_u64 v[250:251], s[48:49], 0, v[144:145]
	s_barrier
	ds_read_b128 v[180:183], v171 offset:16384
	ds_read_b128 v[184:187], v171 offset:17408
	ds_read_b128 v[204:207], v171 offset:18432
	ds_read_b128 v[208:211], v171 offset:19456
	ds_read_b128 v[212:215], v171 offset:20480
	ds_read_b128 v[216:219], v171 offset:21504
	ds_read_b128 v[226:229], v171 offset:22528
	ds_read_b128 v[230:233], v171 offset:23552
	global_load_lds_dwordx4 v[250:251], off
	v_lshl_add_u64 v[162:163], s[48:49], 0, v[140:141]
	s_mov_b32 m0, s97
	s_nop 0
	global_load_lds_dwordx4 v[162:163], off
	s_barrier
	s_waitcnt lgkmcnt(0)
	s_waitcnt lgkmcnt(0)
	v_mfma_f32_16x16x32_bf16 v[62:65], v[150:153], v[180:183], v[62:65]
	v_mfma_f32_16x16x32_bf16 v[58:61], v[172:175], v[180:183], v[58:61]
	v_mfma_f32_16x16x32_bf16 v[46:49], v[150:153], v[204:207], v[46:49]
	v_mfma_f32_16x16x32_bf16 v[42:45], v[172:175], v[204:207], v[42:45]
	v_mfma_f32_16x16x32_bf16 v[30:33], v[150:153], v[212:215], v[30:33]
	v_mfma_f32_16x16x32_bf16 v[26:29], v[172:175], v[212:215], v[26:29]
	v_mfma_f32_16x16x32_bf16 v[14:17], v[150:153], v[226:229], v[14:17]
	v_mfma_f32_16x16x32_bf16 v[10:13], v[172:175], v[226:229], v[10:13]
	v_mfma_f32_16x16x32_bf16 v[62:65], v[154:157], v[184:187], v[62:65]
	v_mfma_f32_16x16x32_bf16 v[58:61], v[176:179], v[184:187], v[58:61]
	v_mfma_f32_16x16x32_bf16 v[46:49], v[154:157], v[208:211], v[46:49]
	v_mfma_f32_16x16x32_bf16 v[42:45], v[176:179], v[208:211], v[42:45]
	v_mfma_f32_16x16x32_bf16 v[30:33], v[154:157], v[216:219], v[30:33]
	v_mfma_f32_16x16x32_bf16 v[26:29], v[176:179], v[216:219], v[26:29]
	v_mfma_f32_16x16x32_bf16 v[14:17], v[154:157], v[230:233], v[14:17]
	v_mfma_f32_16x16x32_bf16 v[10:13], v[176:179], v[230:233], v[10:13]
	s_barrier
; #define PG8_STAGE(bufoff, gbase, voff) do { _Pragma("unroll") for (int _i = 0; _i < 2; ++_i) \
;         __builtin_amdgcn_global_load_lds((const unsigned*)((const char*)(gbase) + (voff)[_i]), (LAS unsigned*)(lds + (bufoff) + ldsw + _i * 8192), 16, 0, 0); } while (0)
; #define PG8_LDA(dst, b, h) do { _Pragma("unroll") for (int m = 0; m < 4; ++m) _Pragma("unroll") for (int k = 0; k < 2; ++k) dst[m][k] = *(const LAS bf16x8*)(lds + PG8_SA(b, h) + aoff + m * 2048 + k * 1024); } while (0)
; #define PG8_LDB(dst, b, h) do { _Pragma("unroll") for (int n = 0; n < 2; ++n) _Pragma("unroll") for (int k = 0; k < 2; ++k) dst[n][k] = *(const LAS bf16x8*)(lds + PG8_SB(b, h) + boff + n * 2048 + k * 1024); } while (0)
; #define PG8_MMA(ai, bj, At, Bt) do { __builtin_amdgcn_s_setprio(1); _Pragma("unroll") for (int m = 0; m < 4; ++m) _Pragma("unroll") for (int n = 0; n < 2; ++n) _Pragma("unroll") for (int k = 0; k < 2; ++k) \
;         acc[ai][bj][m][n] = __builtin_amdgcn_mfma_f32_16x16x32_bf16(Bt[n][k], At[m][k], acc[ai][bj][m][n], 0, 0, 0); __builtin_amdgcn_s_setprio(0); } while (0)
; #define PG8_WAIT_V(n) asm volatile("s_waitcnt vmcnt(" #n ")" ::: "memory")
; #define PG8_WAIT_L(n) asm volatile("s_waitcnt lgkmcnt(" #n ")" ::: "memory")
; #define PG8_BAR __builtin_amdgcn_s_barrier()
; #define PG8_SCHED __builtin_amdgcn_sched_barrier(0)
; template <class Epi>
; __device__ __forceinline__ void gemm_phase(LAS unsigned char* lds, const Gemm g, const StaticOrder& S, const Epi& E) {
;     ...
;             PG8_STAGE(PG8_SB(0, 1), b2 + hstep, voffB);
;             PG8_WAIT_V(6); PG8_BAR; PG8_MMA(1, 1, At, B1); PG8_BAR;
;             PG8_LDB(B0, 1, 0); PG8_SCHED; PG8_LDA(At, 1, 0); PG8_STAGE(PG8_SA(0, 1), a2 + hstep, voffA);
;             PG8_WAIT_L(8); PG8_BAR; PG8_WAIT_L(0); PG8_MMA(0, 0, At, B0); PG8_BAR; PG8_SCHED;
;             PG8_LDB(B1, 1, 1); PG8_STAGE(PG8_SB(1, 0), b3, voffB);
	s_add_u32 s54, s6, 0x40000
	s_addc_u32 s55, s7, 0
	s_add_i32 vcc_lo, vcc_hi, s89
	v_lshl_add_u64 v[150:151], s[54:55], 0, v[142:143]
	s_mov_b32 m0, vcc_lo
	s_nop 0
	global_load_lds_dwordx4 v[150:151], off
	v_lshl_add_u64 v[150:151], s[54:55], 0, v[138:139]
	s_add_i32 m0, vcc_lo, 0x2000
	s_nop 0
	global_load_lds_dwordx4 v[150:151], off
	s_waitcnt vmcnt(6)
	s_barrier
	v_mfma_f32_16x16x32_bf16 v[54:57], v[234:237], v[180:183], v[54:57]
	v_mfma_f32_16x16x32_bf16 v[50:53], v[242:245], v[180:183], v[50:53]
	v_mfma_f32_16x16x32_bf16 v[38:41], v[234:237], v[204:207], v[38:41]
	v_mfma_f32_16x16x32_bf16 v[34:37], v[242:245], v[204:207], v[34:37]
	v_mfma_f32_16x16x32_bf16 v[22:25], v[234:237], v[212:215], v[22:25]
	v_mfma_f32_16x16x32_bf16 v[18:21], v[242:245], v[212:215], v[18:21]
	v_mfma_f32_16x16x32_bf16 v[6:9], v[234:237], v[226:229], v[6:9]
	v_mfma_f32_16x16x32_bf16 v[2:5], v[242:245], v[226:229], v[2:5]
	v_mfma_f32_16x16x32_bf16 v[54:57], v[238:241], v[184:187], v[54:57]
	v_mfma_f32_16x16x32_bf16 v[50:53], v[246:249], v[184:187], v[50:53]
	v_mfma_f32_16x16x32_bf16 v[38:41], v[238:241], v[208:211], v[38:41]
	v_mfma_f32_16x16x32_bf16 v[34:37], v[246:249], v[208:211], v[34:37]
	v_mfma_f32_16x16x32_bf16 v[22:25], v[238:241], v[216:219], v[22:25]
	v_mfma_f32_16x16x32_bf16 v[18:21], v[246:249], v[216:219], v[18:21]
	v_mfma_f32_16x16x32_bf16 v[6:9], v[238:241], v[230:233], v[6:9]
	v_mfma_f32_16x16x32_bf16 v[2:5], v[246:249], v[230:233], v[2:5]
	s_add_i32 s54, 0, 0x18000
	v_add_u32_e32 v0, s54, v168
	s_barrier
	ds_read_b128 v[150:153], v0
	ds_read_b128 v[154:157], v0 offset:1024
	ds_read_b128 v[172:175], v0 offset:2048
	ds_read_b128 v[176:179], v0 offset:3072
	s_add_u32 s48, s48, 0x40000
	s_addc_u32 s49, s49, 0
	s_mov_b32 m0, s83
	v_lshl_add_u64 v[234:235], s[48:49], 0, v[144:145]
	ds_read_b128 v[180:183], v171 offset:32768
	ds_read_b128 v[184:187], v171 offset:33792
	ds_read_b128 v[204:207], v171 offset:34816
	ds_read_b128 v[208:211], v171 offset:35840
	ds_read_b128 v[212:215], v171 offset:36864
	ds_read_b128 v[216:219], v171 offset:37888
	ds_read_b128 v[226:229], v171 offset:38912
	ds_read_b128 v[230:233], v171 offset:39936
	global_load_lds_dwordx4 v[234:235], off
	v_lshl_add_u64 v[234:235], s[48:49], 0, v[140:141]
	s_mov_b32 m0, s88
	s_nop 0
	global_load_lds_dwordx4 v[234:235], off
	s_waitcnt lgkmcnt(8)
	s_barrier
	s_waitcnt lgkmcnt(0)
	s_waitcnt lgkmcnt(0)
	v_mfma_f32_16x16x32_bf16 v[126:129], v[150:153], v[180:183], v[126:129]
	v_mfma_f32_16x16x32_bf16 v[122:125], v[172:175], v[180:183], v[122:125]
	v_mfma_f32_16x16x32_bf16 v[110:113], v[150:153], v[204:207], v[110:113]
	v_mfma_f32_16x16x32_bf16 v[106:109], v[172:175], v[204:207], v[106:109]
	v_mfma_f32_16x16x32_bf16 v[94:97], v[150:153], v[212:215], v[94:97]
	v_mfma_f32_16x16x32_bf16 v[90:93], v[172:175], v[212:215], v[90:93]
	v_mfma_f32_16x16x32_bf16 v[78:81], v[150:153], v[226:229], v[78:81]
	v_mfma_f32_16x16x32_bf16 v[74:77], v[172:175], v[226:229], v[74:77]
	v_mfma_f32_16x16x32_bf16 v[126:129], v[154:157], v[184:187], v[126:129]
	v_mfma_f32_16x16x32_bf16 v[122:125], v[176:179], v[184:187], v[122:125]
	v_mfma_f32_16x16x32_bf16 v[110:113], v[154:157], v[208:211], v[110:113]
	v_mfma_f32_16x16x32_bf16 v[106:109], v[176:179], v[208:211], v[106:109]
	v_mfma_f32_16x16x32_bf16 v[94:97], v[154:157], v[216:219], v[94:97]
	v_mfma_f32_16x16x32_bf16 v[90:93], v[176:179], v[216:219], v[90:93]
	v_mfma_f32_16x16x32_bf16 v[78:81], v[154:157], v[230:233], v[78:81]
	v_mfma_f32_16x16x32_bf16 v[74:77], v[176:179], v[230:233], v[74:77]
	s_barrier
	s_add_i32 s48, 0, 0x1c000
	s_add_i32 s49, s54, s89
	v_add_u32_e32 v0, s48, v168
	v_lshl_add_u64 v[134:135], v[134:135], 0, s[26:27]
	s_mov_b32 m0, s49
	ds_read_b128 v[234:237], v0
	ds_read_b128 v[238:241], v0 offset:1024
	ds_read_b128 v[242:245], v0 offset:2048
	ds_read_b128 v[246:249], v0 offset:3072
	global_load_lds_dwordx4 v[134:135], off
	v_lshl_add_u64 v[134:135], v[220:221], 0, s[26:27]
	s_add_i32 m0, s49, 0x2000
	s_nop 0
	global_load_lds_dwordx4 v[134:135], off
	s_barrier
; #define PG8_STAGE(bufoff, gbase, voff) do { _Pragma("unroll") for (int _i = 0; _i < 2; ++_i) \
;         __builtin_amdgcn_global_load_lds((const unsigned*)((const char*)(gbase) + (voff)[_i]), (LAS unsigned*)(lds + (bufoff) + ldsw + _i * 8192), 16, 0, 0); } while (0)
; #define PG8_LDA(dst, b, h) do { _Pragma("unroll") for (int m = 0; m < 4; ++m) _Pragma("unroll") for (int k = 0; k < 2; ++k) dst[m][k] = *(const LAS bf16x8*)(lds + PG8_SA(b, h) + aoff + m * 2048 + k * 1024); } while (0)
; #define PG8_MMA(ai, bj, At, Bt) do { __builtin_amdgcn_s_setprio(1); _Pragma("unroll") for (int m = 0; m < 4; ++m) _Pragma("unroll") for (int n = 0; n < 2; ++n) _Pragma("unroll") for (int k = 0; k < 2; ++k) \
;         acc[ai][bj][m][n] = __builtin_amdgcn_mfma_f32_16x16x32_bf16(Bt[n][k], At[m][k], acc[ai][bj][m][n], 0, 0, 0); __builtin_amdgcn_s_setprio(0); } while (0)
; #define PG8_WAIT_V(n) asm volatile("s_waitcnt vmcnt(" #n ")" ::: "memory")
; #define PG8_WAIT_L(n) asm volatile("s_waitcnt lgkmcnt(" #n ")" ::: "memory")
; #define PG8_BAR __builtin_amdgcn_s_barrier()
; #define PG8_SCHED __builtin_amdgcn_sched_barrier(0)
; template <class Epi>
; __device__ __forceinline__ void gemm_phase(LAS unsigned char* lds, const Gemm g, const StaticOrder& S, const Epi& E) {
;     ...
;             PG8_BAR; PG8_WAIT_L(0); PG8_MMA(0, 1, At, B1); PG8_BAR;
;             PG8_LDA(At, 1, 1); PG8_STAGE(PG8_SA(1, 0), a3, voffA);
;             PG8_BAR; PG8_WAIT_L(0); PG8_MMA(1, 0, At, B0); PG8_BAR; PG8_SCHED;
;             PG8_STAGE(PG8_SB(1, 1), b3 + hstep, voffB);
;             PG8_WAIT_V(6); PG8_BAR; PG8_MMA(1, 1, At, B1); PG8_BAR;
;         }
	s_waitcnt lgkmcnt(0)
	s_waitcnt lgkmcnt(0)
	v_mfma_f32_16x16x32_bf16 v[118:121], v[234:237], v[180:183], v[118:121]
	v_mfma_f32_16x16x32_bf16 v[114:117], v[242:245], v[180:183], v[114:117]
	v_mfma_f32_16x16x32_bf16 v[102:105], v[234:237], v[204:207], v[102:105]
	v_mfma_f32_16x16x32_bf16 v[98:101], v[242:245], v[204:207], v[98:101]
	v_mfma_f32_16x16x32_bf16 v[86:89], v[234:237], v[212:215], v[86:89]
	v_mfma_f32_16x16x32_bf16 v[82:85], v[242:245], v[212:215], v[82:85]
	v_mfma_f32_16x16x32_bf16 v[70:73], v[234:237], v[226:229], v[70:73]
	v_mfma_f32_16x16x32_bf16 v[66:69], v[242:245], v[226:229], v[66:69]
	v_mfma_f32_16x16x32_bf16 v[118:121], v[238:241], v[184:187], v[118:121]
	v_mfma_f32_16x16x32_bf16 v[114:117], v[246:249], v[184:187], v[114:117]
	v_mfma_f32_16x16x32_bf16 v[102:105], v[238:241], v[208:211], v[102:105]
	v_mfma_f32_16x16x32_bf16 v[98:101], v[246:249], v[208:211], v[98:101]
	v_mfma_f32_16x16x32_bf16 v[86:89], v[238:241], v[216:219], v[86:89]
	v_mfma_f32_16x16x32_bf16 v[82:85], v[246:249], v[216:219], v[82:85]
	v_mfma_f32_16x16x32_bf16 v[70:73], v[238:241], v[230:233], v[70:73]
	v_mfma_f32_16x16x32_bf16 v[66:69], v[246:249], v[230:233], v[66:69]
	s_mov_b32 m0, s85
	v_lshl_add_u64 v[134:135], v[250:251], 0, s[26:27]
	s_barrier
	ds_read_b128 v[180:183], v171 offset:49152
	ds_read_b128 v[184:187], v171 offset:50176
	ds_read_b128 v[204:207], v171 offset:51200
	ds_read_b128 v[208:211], v171 offset:52224
	ds_read_b128 v[212:215], v171 offset:53248
	ds_read_b128 v[216:219], v171 offset:54272
	ds_read_b128 v[226:229], v171 offset:55296
	ds_read_b128 v[230:233], v171 offset:56320
	global_load_lds_dwordx4 v[134:135], off
	v_lshl_add_u64 v[134:135], v[162:163], 0, s[26:27]
	s_mov_b32 m0, s86
	s_nop 0
	global_load_lds_dwordx4 v[134:135], off
	s_barrier
	s_waitcnt lgkmcnt(0)
	s_waitcnt lgkmcnt(0)
	v_mfma_f32_16x16x32_bf16 v[62:65], v[150:153], v[180:183], v[62:65]
	v_mfma_f32_16x16x32_bf16 v[58:61], v[172:175], v[180:183], v[58:61]
	v_mfma_f32_16x16x32_bf16 v[46:49], v[150:153], v[204:207], v[46:49]
	v_mfma_f32_16x16x32_bf16 v[42:45], v[172:175], v[204:207], v[42:45]
	v_mfma_f32_16x16x32_bf16 v[30:33], v[150:153], v[212:215], v[30:33]
	v_mfma_f32_16x16x32_bf16 v[26:29], v[172:175], v[212:215], v[26:29]
	v_mfma_f32_16x16x32_bf16 v[14:17], v[150:153], v[226:229], v[14:17]
	v_mfma_f32_16x16x32_bf16 v[10:13], v[172:175], v[226:229], v[10:13]
	v_mfma_f32_16x16x32_bf16 v[62:65], v[154:157], v[184:187], v[62:65]
	v_mfma_f32_16x16x32_bf16 v[58:61], v[176:179], v[184:187], v[58:61]
	v_mfma_f32_16x16x32_bf16 v[46:49], v[154:157], v[208:211], v[46:49]
	v_mfma_f32_16x16x32_bf16 v[42:45], v[176:179], v[208:211], v[42:45]
	v_mfma_f32_16x16x32_bf16 v[30:33], v[154:157], v[216:219], v[30:33]
	v_mfma_f32_16x16x32_bf16 v[26:29], v[176:179], v[216:219], v[26:29]
	v_mfma_f32_16x16x32_bf16 v[14:17], v[154:157], v[230:233], v[14:17]
	v_mfma_f32_16x16x32_bf16 v[10:13], v[176:179], v[230:233], v[10:13]
	s_barrier
	s_add_u32 s6, s6, 0x40080
	s_addc_u32 s7, s7, 0
	s_add_i32 s48, s48, s89
	v_lshl_add_u64 v[134:135], s[6:7], 0, v[142:143]
	s_mov_b32 m0, s48
	s_nop 0
	global_load_lds_dwordx4 v[134:135], off
	v_lshl_add_u64 v[134:135], s[6:7], 0, v[138:139]
	s_add_i32 m0, s48, 0x2000
	s_nop 0
	global_load_lds_dwordx4 v[134:135], off
	s_waitcnt vmcnt(6)
	s_barrier
	v_mfma_f32_16x16x32_bf16 v[54:57], v[234:237], v[180:183], v[54:57]
	v_mfma_f32_16x16x32_bf16 v[50:53], v[242:245], v[180:183], v[50:53]
	v_mfma_f32_16x16x32_bf16 v[38:41], v[234:237], v[204:207], v[38:41]
	v_mfma_f32_16x16x32_bf16 v[34:37], v[242:245], v[204:207], v[34:37]
	v_mfma_f32_16x16x32_bf16 v[22:25], v[234:237], v[212:215], v[22:25]
	v_mfma_f32_16x16x32_bf16 v[18:21], v[242:245], v[212:215], v[18:21]
	v_mfma_f32_16x16x32_bf16 v[6:9], v[234:237], v[226:229], v[6:9]
	v_mfma_f32_16x16x32_bf16 v[2:5], v[242:245], v[226:229], v[2:5]
	v_mfma_f32_16x16x32_bf16 v[54:57], v[238:241], v[184:187], v[54:57]
	v_mfma_f32_16x16x32_bf16 v[50:53], v[246:249], v[184:187], v[50:53]
	v_mfma_f32_16x16x32_bf16 v[38:41], v[238:241], v[208:211], v[38:41]
	v_mfma_f32_16x16x32_bf16 v[34:37], v[246:249], v[208:211], v[34:37]
	v_mfma_f32_16x16x32_bf16 v[22:25], v[238:241], v[216:219], v[22:25]
	v_mfma_f32_16x16x32_bf16 v[18:21], v[246:249], v[216:219], v[18:21]
	v_mfma_f32_16x16x32_bf16 v[6:9], v[238:241], v[230:233], v[6:9]
	v_mfma_f32_16x16x32_bf16 v[2:5], v[246:249], v[230:233], v[2:5]
	s_add_i32 s6, s70, 2
	s_add_u32 s46, s46, 0x100
	s_addc_u32 s47, s47, 0
	s_cmp_gt_u32 s70, 13
	s_barrier
	s_cbranch_scc1 .LBB0_209
	s_mov_b32 s70, s6
	s_cmp_lt_i32 s70, 8
	s_cbranch_scc1 .LBB0_201
	s_branch .LBB0_200

; #define PG8_WAIT_V(n) asm volatile("s_waitcnt vmcnt(" #n ")" ::: "memory")
; #define PG8_BAR __builtin_amdgcn_s_barrier()
; template <class Epi>
; __device__ __forceinline__ void gemm_phase(LAS unsigned char* lds, const Gemm g, const StaticOrder& S, const Epi& E) {
;     ...
;     PG8_WAIT_V(0);
;     if (wr == 0) PG8_BAR;
;     PG8_BAR;
.LBB0_227:
	s_setprio 0
	v_readlane_b32 s84, v253, 0
	s_barrier
	v_readlane_b32 s85, v253, 1
